# v27 + NSA stage C: K/V block loads as global loads with counted vmcnt waits (loop top waits only for K, V waited before first PV MFMA)
# speedup vs baseline: 1.0069x; 1.0030x over previous
; DI void nsa_phase(unsigned char* lds, KParamPtr P, int wv) {
;     ...
;         auto load_k = [&](int jb) {
;           const unsigned ko = kbase + (unsigned)(jb * 64 * EIN);
; #pragma unroll
;           for (int hf = 0; hf < 2; ++hf)
; #pragma unroll
;             for (int tl = 0; tl < 2; ++tl) {
;               kf[(hf * 2 + tl) * 2 + 0] = ldg8(proj + ko + (unsigned)((hf * 32 + 4 * tl) * EIN));
;               kf[(hf * 2 + tl) * 2 + 1] = ldg8(proj + ko + (unsigned)((hf * 32 + 4 * tl) * EIN + 32));
;             }
;         };
;         auto load_v = [&](int jb) {
;           const unsigned vo = vbase + (unsigned)(jb * 64);
; #pragma unroll
;           for (int hf = 0; hf < 2; ++hf)
; #pragma unroll
;             for (int e = 0; e < 4; ++e) vf[hf * 4 + e] = ldg8(vsT + vo + (unsigned)(e * 16 * SEQ + hf * 32));
;         };
;         int jb = next_blk();
;         if (jb >= 0) { load_k(jb); load_v(jb); }
.LBB0_1092:
	v_lshl_add_u32 v0, v136, 12, v123
	v_lshl_add_u64 v[14:15], v[0:1], 1, s[20:21]
	v_add_co_u32_e32 v16, vcc, 0, v14
	global_load_dwordx4 v[50:53], v[14:15], off
	global_load_dwordx4 v[54:57], v[14:15], off offset:1024
	v_addc_co_u32_e32 v17, vcc, 0, v15, vcc
	global_load_dwordx4 v[58:61], v[16:17], off offset:2048
	global_load_dwordx4 v[62:65], v[16:17], off offset:3072
	v_add_co_u32_e32 v16, vcc, 0x1000, v14
	v_lshlrev_b32_e32 v0, 12, v136
	s_nop 0
	v_addc_co_u32_e32 v17, vcc, 0, v15, vcc
	v_add_co_u32_e32 v14, vcc, 0x1000, v14
	v_add_lshl_u32 v0, v0, v124, 1
	s_nop 0
	v_addc_co_u32_e32 v15, vcc, 0, v15, vcc
	global_load_dwordx4 v[66:69], v[16:17], off
	global_load_dwordx4 v[70:73], v[16:17], off offset:1024
	global_load_dwordx4 v[74:77], v[14:15], off offset:2048
	global_load_dwordx4 v[78:81], v[14:15], off offset:3072
	v_lshl_add_u64 v[14:15], s[22:23], 0, v[0:1]
	v_add_co_u32_e32 v16, vcc, 0x800, v14
	s_nop 1
	v_addc_co_u32_e32 v17, vcc, 0, v15, vcc
	v_add_co_u32_e32 v18, vcc, 0x1000, v14
	s_nop 1
	v_addc_co_u32_e32 v19, vcc, 0, v15, vcc
	v_add_co_u32_e32 v20, vcc, 0x1800, v14
	s_nop 1
	v_addc_co_u32_e32 v21, vcc, 0, v15, vcc
	global_load_dwordx4 v[82:85], v[14:15], off
	global_load_dwordx4 v[86:89], v[14:15], off offset:1024
	global_load_dwordx4 v[94:97], v[16:17], off
	global_load_dwordx4 v[90:93], v[16:17], off offset:1024
	global_load_dwordx4 v[102:105], v[18:19], off
	global_load_dwordx4 v[98:101], v[18:19], off offset:1024
	global_load_dwordx4 v[110:113], v[20:21], off
	global_load_dwordx4 v[106:109], v[20:21], off offset:1024

; #define MFMA16(a, b, c) __builtin_amdgcn_mfma_f32_16x16x32_bf16((a), (b), (c), 0, 0, 0)
; DI void nsa_phase(unsigned char* lds, KParamPtr P, int wv) {
;     ...
;         auto next_blk = [&]() -> int {
;           if (u0) { int bq = __builtin_ctz(u0); u0 &= u0 - 1u; return bq; }
;           if (u1) { int bq = __builtin_ctz(u1); u1 &= u1 - 1u; return 32 + bq; }
;           if (u2) { int bq = __builtin_ctz(u2); u2 &= u2 - 1u; return 64 + bq; }
;           if (u3) { int bq = __builtin_ctz(u3); u3 &= u3 - 1u; return 96 + bq; }
;           return -1;
;         };
;     ...
;         while (jb >= 0) {
;           const int base = jb * 64;
;           const unsigned mw = jb < 32 ? mym.x : (jb < 64 ? mym.y : (jb < 96 ? mym.z : mym.w));
;           const bool member = (mw >> (jb & 31)) & 1u;
;           f32x4 a[2][2];
; #pragma unroll
;           for (int hf = 0; hf < 2; ++hf)
; #pragma unroll
;             for (int tl = 0; tl < 2; ++tl) {
;               f32x4 acc = (f32x4){0.f, 0.f, 0.f, 0.f};
;               acc = MFMA16(kf[(hf * 2 + tl) * 2 + 0], qf[0], acc);
;               acc = MFMA16(kf[(hf * 2 + tl) * 2 + 1], qf[1], acc);
;               a[hf][tl] = acc;
;             }
;           const int jn = next_blk();
.LBB0_1096:
	s_waitcnt vmcnt(8) lgkmcnt(0)
	v_mfma_f32_16x16x32_bf16 v[30:33], v[50:53], v[6:9], 0
	v_cmp_ne_u32_e32 vcc, 0, v121
	v_mfma_f32_16x16x32_bf16 v[42:45], v[54:57], v[10:13], v[30:33]
	v_mfma_f32_16x16x32_bf16 v[30:33], v[58:61], v[6:9], 0
	v_mfma_f32_16x16x32_bf16 v[38:41], v[62:65], v[10:13], v[30:33]
	v_mfma_f32_16x16x32_bf16 v[30:33], v[66:69], v[6:9], 0
	v_mfma_f32_16x16x32_bf16 v[34:37], v[70:73], v[10:13], v[30:33]
	v_mfma_f32_16x16x32_bf16 v[30:33], v[74:77], v[6:9], 0
	v_mfma_f32_16x16x32_bf16 v[30:33], v[78:81], v[10:13], v[30:33]
	s_and_saveexec_b64 s[12:13], vcc
	s_xor_b64 s[12:13], exec, s[12:13]
	v_add_u32_e32 v0, -1, v121
	v_ffbl_b32_e32 v134, v121
	v_and_b32_e32 v121, v0, v121
	s_andn2_saveexec_b64 s[12:13], s[12:13]
	s_cbranch_execz .LBB0_1108
	v_cmp_ne_u32_e32 vcc, 0, v131
	s_and_saveexec_b64 s[14:15], vcc
	s_xor_b64 s[14:15], exec, s[14:15]
	v_ffbl_b32_e32 v0, v131
	v_add_u32_e32 v121, -1, v131
	v_and_b32_e32 v131, v121, v131
	v_or_b32_e32 v134, 32, v0
	s_andn2_saveexec_b64 s[14:15], s[14:15]
	s_cbranch_execz .LBB0_1107
	v_cmp_ne_u32_e32 vcc, 0, v130
	s_and_saveexec_b64 s[16:17], vcc
	s_xor_b64 s[16:17], exec, s[16:17]
	v_ffbl_b32_e32 v0, v130
	v_add_u32_e32 v121, -1, v130
	v_and_b32_e32 v130, v121, v130
	v_or_b32_e32 v134, 64, v0
	s_andn2_saveexec_b64 s[16:17], s[16:17]
	v_ffbl_b32_e32 v0, v129
	v_or_b32_e32 v0, 0x60, v0
	v_subrev_co_u32_e32 v121, vcc, 1, v129
	v_and_b32_e32 v129, v121, v129
	s_nop 0
	v_cndmask_b32_e64 v134, v0, -1, vcc
	v_mov_b32_e32 v130, 0
	s_or_b64 exec, exec, s[16:17]
	v_mov_b32_e32 v131, 0

; DI void nsa_phase(unsigned char* lds, KParamPtr P, int wv) {
;     ...
;         auto load_k = [&](int jb) {
;           const unsigned ko = kbase + (unsigned)(jb * 64 * EIN);
; #pragma unroll
;           for (int hf = 0; hf < 2; ++hf)
; #pragma unroll
;             for (int tl = 0; tl < 2; ++tl) {
;               kf[(hf * 2 + tl) * 2 + 0] = ldg8(proj + ko + (unsigned)((hf * 32 + 4 * tl) * EIN));
;               kf[(hf * 2 + tl) * 2 + 1] = ldg8(proj + ko + (unsigned)((hf * 32 + 4 * tl) * EIN + 32));
;             }
;         };
;     ...
;           const int jn = next_blk();
;           if (jn >= 0) load_k(jn);
.LBB0_1108:
	s_or_b64 exec, exec, s[12:13]
	v_cmp_lt_i32_e64 s[14:15], -1, v134
	v_cmp_gt_i32_e64 s[12:13], 0, v134
	s_and_saveexec_b64 s[16:17], s[14:15]
	s_cbranch_execz .LBB0_1110
	v_lshl_add_u32 v0, v134, 12, v123
	v_lshl_add_u64 v[74:75], v[0:1], 1, s[20:21]
	v_add_co_u32_e32 v62, vcc, 0, v74
	global_load_dwordx4 v[50:53], v[74:75], off
	global_load_dwordx4 v[54:57], v[74:75], off offset:1024
	v_addc_co_u32_e32 v63, vcc, 0, v75, vcc
	v_add_co_u32_e32 v70, vcc, 0x1000, v74
	global_load_dwordx4 v[58:61], v[62:63], off offset:2048
	s_nop 0
	global_load_dwordx4 v[62:65], v[62:63], off offset:3072
	v_addc_co_u32_e32 v71, vcc, 0, v75, vcc
	v_add_co_u32_e32 v78, vcc, 0x1000, v74
	global_load_dwordx4 v[66:69], v[70:71], off
	s_nop 0
	global_load_dwordx4 v[70:73], v[70:71], off offset:1024
	v_addc_co_u32_e32 v79, vcc, 0, v75, vcc
	global_load_dwordx4 v[74:77], v[78:79], off offset:2048
	s_nop 0
	global_load_dwordx4 v[78:81], v[78:79], off offset:3072

; #define MFMA16(a, b, c) __builtin_amdgcn_mfma_f32_16x16x32_bf16((a), (b), (c), 0, 0, 0)
; DI unsigned pk2(float a, float b) { f32x2 v = {a, b}; bfx2 r = __builtin_convertvector(v, bfx2); return __builtin_bit_cast(unsigned, r); }
; DI float ex2(float x) { return __builtin_amdgcn_exp2f(x); }
; DI float red_max32(float x) { auto r = __builtin_amdgcn_permlane32_swap(__float_as_uint(x), __float_as_uint(x), false, false); return fmaxf(__uint_as_float(r[0]), __uint_as_float(r[1])); }
; DI float red_max16(float x) { auto r = __builtin_amdgcn_permlane16_swap(__float_as_uint(x), __float_as_uint(x), false, false); return fmaxf(__uint_as_float(r[0]), __uint_as_float(r[1])); }
; DI void nsa_phase(unsigned char* lds, KParamPtr P, int wv) {
;     ...
;           mloc = red_max16(mloc);
;           mloc = red_max32(mloc);
;           const float mn = fmaxf(m, mloc);
;           const float alpha = ex2(m - mn);
;           float ls = 0.f;
; #pragma unroll
;           for (int hf = 0; hf < 2; ++hf)
; #pragma unroll
;             for (int tl = 0; tl < 2; ++tl)
; #pragma unroll
;               for (int j = 0; j < 4; ++j) { float p = (a[hf][tl][j] > -1e29f) ? ex2(a[hf][tl][j] - mn) : 0.f; a[hf][tl][j] = p; ls += p; }
;           l = l * alpha + ls; m = mn;
; #pragma unroll
;           for (int e = 0; e < 4; ++e) O[e] *= alpha;
; #pragma unroll
;           for (int hf = 0; hf < 2; ++hf) {
;             u32x4 u; u.x = pk2(a[hf][0][0], a[hf][0][1]); u.y = pk2(a[hf][0][2], a[hf][0][3]); u.z = pk2(a[hf][1][0], a[hf][1][1]); u.w = pk2(a[hf][1][2], a[hf][1][3]);
;             const bf16x8 pf = __builtin_bit_cast(bf16x8, u);
; #pragma unroll
;             for (int e = 0; e < 4; ++e) O[e] = MFMA16(vf[hf * 4 + e], pf, O[e]);
;           }
;           if (jn >= 0) load_v(jn);
;           jb = jn;
.LBB0_1146:
	s_or_b64 exec, exec, s[16:17]
	v_mov_b32_e32 v30, v151
	s_nop 1
	v_permlane16_swap_b32_e32 v151, v30
	v_max_f32_e32 v30, v30, v30
	v_max_f32_e32 v31, v151, v151
	v_max_f32_e32 v30, v31, v30
	v_mov_b32_e32 v31, v30
	s_nop 1
	v_permlane32_swap_b32_e32 v30, v31
	v_max3_f32 v31, v135, v30, v31
	v_sub_f32_e32 v32, v137, v31
	v_exp_f32_e32 v32, v32
	v_cmp_lt_f32_e32 vcc, s62, v137
	v_sub_f32_e32 v30, v135, v31
	v_exp_f32_e32 v30, v30
	v_cndmask_b32_e32 v32, 0, v32, vcc
	v_cmp_lt_f32_e32 vcc, s62, v0
	v_sub_f32_e32 v0, v0, v31
	v_exp_f32_e32 v0, v0
	v_pk_mul_f32 v[28:29], v[28:29], v[30:31] op_sel_hi:[1,0]
	v_pk_mul_f32 v[26:27], v[26:27], v[30:31] op_sel_hi:[1,0]
	v_pk_mul_f32 v[24:25], v[24:25], v[30:31] op_sel_hi:[1,0]
	v_cndmask_b32_e32 v33, 0, v0, vcc
	v_sub_f32_e32 v0, v138, v31
	v_exp_f32_e32 v0, v0
	v_cmp_lt_f32_e32 vcc, s62, v138
	v_pk_mul_f32 v[22:23], v[22:23], v[30:31] op_sel_hi:[1,0]
	v_pk_mul_f32 v[20:21], v[20:21], v[30:31] op_sel_hi:[1,0]
	v_cndmask_b32_e32 v34, 0, v0, vcc
	v_sub_f32_e32 v0, v136, v31
	v_exp_f32_e32 v0, v0
	v_cmp_lt_f32_e32 vcc, s62, v136
	v_pk_mul_f32 v[18:19], v[18:19], v[30:31] op_sel_hi:[1,0]
	v_pk_mul_f32 v[16:17], v[16:17], v[30:31] op_sel_hi:[1,0]
	v_cndmask_b32_e32 v35, 0, v0, vcc
	v_sub_f32_e32 v0, v141, v31
	v_exp_f32_e32 v0, v0
	v_cmp_lt_f32_e32 vcc, s62, v141
	v_pk_mul_f32 v[14:15], v[14:15], v[30:31] op_sel_hi:[1,0]
	v_cvt_pk_bf16_f32 v138, v32, v33
	v_cndmask_b32_e32 v36, 0, v0, vcc
	v_sub_f32_e32 v0, v139, v31
	v_exp_f32_e32 v0, v0
	v_cmp_lt_f32_e32 vcc, s62, v139
	v_cvt_pk_bf16_f32 v139, v34, v35
	s_nop 0
	v_cndmask_b32_e32 v37, 0, v0, vcc
	v_sub_f32_e32 v0, v142, v31
	v_exp_f32_e32 v0, v0
	v_cmp_lt_f32_e32 vcc, s62, v142
	s_nop 1
	v_cndmask_b32_e32 v38, 0, v0, vcc
	v_sub_f32_e32 v0, v140, v31
	v_exp_f32_e32 v0, v0
	v_cmp_lt_f32_e32 vcc, s62, v140
	v_cvt_pk_bf16_f32 v140, v36, v37
	s_nop 0
	v_cndmask_b32_e32 v39, 0, v0, vcc
	v_sub_f32_e32 v0, v145, v31
	v_exp_f32_e32 v0, v0
	v_cmp_lt_f32_e32 vcc, s62, v145
	v_cvt_pk_bf16_f32 v141, v38, v39
	s_nop 0
	v_cndmask_b32_e32 v40, 0, v0, vcc
	v_sub_f32_e32 v0, v143, v31
	v_exp_f32_e32 v0, v0
	v_cmp_lt_f32_e32 vcc, s62, v143
	s_cmp_eq_u64 s[14:15], 0
	s_cbranch_scc1 .Lcw_all
	s_waitcnt vmcnt(8)
	s_branch .Lcw_done
.Lcw_all:
	s_waitcnt vmcnt(0)
.Lcw_done:
	v_mfma_f32_16x16x32_bf16 v[26:29], v[82:85], v[138:141], v[26:29]
	s_nop 0
	v_cndmask_b32_e32 v41, 0, v0, vcc
	v_sub_f32_e32 v0, v146, v31
	v_exp_f32_e32 v0, v0
	v_cmp_lt_f32_e32 vcc, s62, v146
	v_mfma_f32_16x16x32_bf16 v[22:25], v[94:97], v[138:141], v[22:25]
	s_nop 0
	v_cndmask_b32_e32 v42, 0, v0, vcc
	v_sub_f32_e32 v0, v144, v31
	v_exp_f32_e32 v0, v0
	v_cmp_lt_f32_e32 vcc, s62, v144
	v_mfma_f32_16x16x32_bf16 v[18:21], v[102:105], v[138:141], v[18:21]
	s_nop 0
	v_cndmask_b32_e32 v43, 0, v0, vcc
	v_sub_f32_e32 v0, v148, v31
	v_exp_f32_e32 v0, v0
	v_cmp_lt_f32_e32 vcc, s62, v148
	v_mfma_f32_16x16x32_bf16 v[14:17], v[110:113], v[138:141], v[14:17]
	v_cvt_pk_bf16_f32 v138, v40, v41
	v_cndmask_b32_e32 v44, 0, v0, vcc
	v_sub_f32_e32 v0, v147, v31
	v_exp_f32_e32 v0, v0
	v_cmp_lt_f32_e32 vcc, s62, v147
	v_cvt_pk_bf16_f32 v139, v42, v43
	s_nop 0
	v_cndmask_b32_e32 v45, 0, v0, vcc
	v_sub_f32_e32 v0, v150, v31
	v_exp_f32_e32 v0, v0
	v_cmp_lt_f32_e32 vcc, s62, v150
	v_cvt_pk_bf16_f32 v140, v44, v45
	s_nop 0
	v_cndmask_b32_e32 v135, 0, v0, vcc
	v_sub_f32_e32 v0, v149, v31
	v_exp_f32_e32 v0, v0
	v_cmp_lt_f32_e32 vcc, s62, v149
	s_nop 1
	v_cndmask_b32_e32 v136, 0, v0, vcc
	v_cvt_pk_bf16_f32 v141, v135, v136
	s_nop 1
	v_mfma_f32_16x16x32_bf16 v[26:29], v[86:89], v[138:141], v[26:29]
	v_mfma_f32_16x16x32_bf16 v[22:25], v[90:93], v[138:141], v[22:25]
	v_mfma_f32_16x16x32_bf16 v[18:21], v[98:101], v[138:141], v[18:21]
	v_mfma_f32_16x16x32_bf16 v[14:17], v[106:109], v[138:141], v[14:17]
	s_and_saveexec_b64 s[16:17], s[14:15]
	s_cbranch_execz .LBB0_1095
	v_lshlrev_b32_e32 v0, 12, v134
	v_add_lshl_u32 v0, v0, v124, 1
	v_lshl_add_u64 v[86:87], s[22:23], 0, v[0:1]
	v_add_co_u32_e32 v90, vcc, 0x800, v86
	s_nop 1
	v_addc_co_u32_e32 v91, vcc, 0, v87, vcc
	v_add_co_u32_e32 v98, vcc, 0x1000, v86
	s_nop 1
	v_addc_co_u32_e32 v99, vcc, 0, v87, vcc
	v_add_co_u32_e32 v106, vcc, 0x1800, v86
	s_nop 1
	v_addc_co_u32_e32 v107, vcc, 0, v87, vcc
	global_load_dwordx4 v[82:85], v[86:87], off
	s_nop 0
	global_load_dwordx4 v[86:89], v[86:87], off offset:1024
	s_nop 0
	global_load_dwordx4 v[94:97], v[90:91], off
	s_nop 0
	global_load_dwordx4 v[90:93], v[90:91], off offset:1024
	s_nop 0
	global_load_dwordx4 v[102:105], v[98:99], off
	s_nop 0
	global_load_dwordx4 v[98:101], v[98:99], off offset:1024
	s_nop 0
	global_load_dwordx4 v[110:113], v[106:107], off
	s_nop 0
	global_load_dwordx4 v[106:109], v[106:107], off offset:1024
	s_branch .LBB0_1095
